# stacked: v76 plus peeled C=0 K-loop first iteration, NSA selection-row registers and batched LIST reads, NSA q-load hoist
# baseline (speedup 1.0000x reference)
; #define LAS __attribute__((address_space(3)))
; #define ST_V(base, v) do { LAS unsigned char* vp_ = (base) + voff; *(LAS u32x2*)vp_ = (u32x2){(v).x, (v).y}; *(LAS u32x2*)(vp_ + 8) = (u32x2){(v).z, (v).w}; } while (0)
; DI void nsa_unit(const Params& p, LAS unsigned char* lds, unsigned char* ldsg, int bg, int qt, int tid) {
;     ...
;         f32x16 o[2];
; #pragma unroll
;         for (int db = 0; db < 2; ++db)
; #pragma unroll
;             for (int i = 0; i < 16; ++i) o[db][i] = 0.f;
;         float m = -1e20f, l = 0.f;
;         u32x4 rk1, rv1, rk2, rv2;
;         { const int nb = LIST[0]; rk1 = *(const u32x4*)(Ksrc + (size_t)(64 * nb) * NPROJ); rv1 = *(const u32x4*)(Vsrc + 64 * nb); }
;         *(LAS u32x4*)(lds + toff) = rk1; ST_V(lds, rv1);
;         if (nl > 1) { const int nb = LIST[1]; rk1 = *(const u32x4*)(Ksrc + (size_t)(64 * nb) * NPROJ); rv1 = *(const u32x4*)(Vsrc + 64 * nb); }
;         __syncthreads();
;         int cb = 0;
;         for (int i = 0; i < nl; ++i) {
;             const int nb = LIST[i];
;             if (i + 2 < nl) { const int nb2 = LIST[i + 2]; rk2 = *(const u32x4*)(Ksrc + (size_t)(64 * nb2) * NPROJ); rv2 = *(const u32x4*)(Vsrc + 64 * nb2); }
;             const bool lanesel = (SEL[(4 * w + qi) * 4 + (nb >> 5)] >> (nb & 31)) & 1u;
.LBB0_818:
	s_movk_i32 s2, 0x88
	s_cmp_lt_i32 s8, 1
	v_mul_u32_u24_e32 v15, 0x88, v68
	v_mad_u32_u24 v176, v68, s2, v168
	s_waitcnt lgkmcnt(0)
	s_barrier
	s_cbranch_scc1 .LBB0_839
	v_or_b32_e32 v10, s49, v67
	s_add_i32 s2, 0, 0x26400
	v_lshl_add_u32 v113, v10, 4, s2
	v_lshlrev_b32_e32 v10, 2, v114
	v_mov_b32_e32 v175, 0
	v_sub_u32_e32 v117, v150, v10
	v_mov_b32_e32 v153, v152
	v_mov_b32_e32 v118, 0xe0ad78ec
	v_mov_b32_e32 v252, 0xe0ad78ec
	v_mov_b32_e32 v248, 0
	s_mov_b32 s9, 0
	v_readlane_b32 s10, v234, 35
	s_mov_b32 s11, 0
	v_mov_b32_e32 v48, 0
	v_mov_b32_e32 v49, v175
	v_mov_b32_e32 v50, v175
	v_mov_b32_e32 v51, v175
	v_mov_b32_e32 v52, v175
	v_mov_b32_e32 v53, v175
	v_mov_b32_e32 v54, v175
	v_mov_b32_e32 v55, v175
	v_mov_b32_e32 v56, v175
	v_mov_b32_e32 v57, v175
	v_mov_b32_e32 v58, v175
	v_mov_b32_e32 v59, v175
	v_mov_b32_e32 v60, v175
	v_mov_b32_e32 v61, v175
	v_mov_b32_e32 v62, v175
	v_mov_b32_e32 v63, v175
	v_mov_b32_e32 v64, v175
	v_mov_b32_e32 v65, v175
	v_mov_b32_e32 v66, v175
	v_mov_b32_e32 v67, v175
	v_mov_b32_e32 v68, v175
	v_mov_b32_e32 v69, v175
	v_mov_b32_e32 v70, v175
	v_mov_b32_e32 v71, v175
	v_mov_b32_e32 v72, v175
	v_mov_b32_e32 v73, v175
	v_mov_b32_e32 v74, v175
	v_mov_b32_e32 v75, v175
	v_mov_b32_e32 v76, v175
	v_mov_b32_e32 v77, v175
	v_mov_b32_e32 v78, v175
	v_mov_b32_e32 v79, v175
	ds_read_b128 v[230:233], v113

; #define LAS __attribute__((address_space(3)))
; #define MFMA32(a, b, c) __builtin_amdgcn_mfma_f32_32x32x16_bf16((a), (b), (c), 0, 0, 0)
; template <int MODE>
; DI void nsa_tile(LAS const unsigned char* buf, const bf16x8 (&qf)[4], f32x16 (&o)[2], float& m, float& l, int kbase0, int t, bool lanesel, float slope2, int c, int hi) {
;     ...
;         if (MODE == 0) { full = lanesel && (klo + 31 <= t); none = !lanesel || (klo > t); }
;         else { full = (klo + 31 <= t) && (klo >= t - 511); none = (klo > t) || (klo + 31 < t - 511); }
;         if (__all(none)) continue;
;         int dbase = t - klo - 4 * hi;
;         asm volatile("" : "+v"(dbase));
;         const float b0 = none ? -1e30f : -slope2 * (float)dbase;
;         f32x16 s;
; #pragma unroll
;         for (int i = 0; i < 16; ++i) s[i] = fmaf(slope2, (float)((i & 3) + 8 * (i >> 2)), b0);
; #pragma unroll
;         for (int st = 0; st < 4; ++st) {
;             const bf16x8 a = *(LAS const bf16x8*)(buf + (32 * sub + c) * 144 + st * 32 + hi * 16);
;             s = MFMA32(a, qf[st], s);
;         }
;         if (__any(!full && !none)) {
; #pragma unroll
;             for (int i = 0; i < 16; ++i) {
;                 const int dist = dbase - ((i & 3) + 8 * (i >> 2));
;                 const bool valid = (MODE == 0) ? (lanesel && dist >= 0) : ((unsigned)dist < 512u);
;                 if (!valid) s[i] = -1e30f;
;             }
; DI void nsa_unit(const Params& p, LAS unsigned char* lds, unsigned char* ldsg, int bg, int qt, int tid) {
;     ...
;             const bool lanesel = (SEL[(4 * w + qi) * 4 + (nb >> 5)] >> (nb & 31)) & 1u;
;             if (__any(lanesel))
;                 nsa_tile<0>(lds + cb * NSA_TBUF, qf, o, m, l, 64 * nb, t, lanesel, slope2, c, hi);
.LBB0_822:
	s_ashr_i32 s2, s4, 5
	s_cmp_eq_u32 s2, 1
	s_cselect_b64 s[98:99], -1, 0
	v_cndmask_b32_e64 v80, v230, v231, s[98:99]
	s_cmp_eq_u32 s2, 2
	s_cselect_b64 s[100:101], -1, 0
	v_cndmask_b32_e64 v80, v80, v232, s[100:101]
	s_cmp_eq_u32 s2, 3
	s_cselect_b64 s[98:99], -1, 0
	v_cndmask_b32_e64 v80, v80, v233, s[98:99]
	s_and_b32 s2, s4, 31
	v_lshrrev_b32_e32 v81, s4, v80
	v_bfe_u32 v80, v80, s2, 1
	v_and_b32_e32 v81, 1, v81
	v_cmp_ne_u32_e32 vcc, 0, v80
	v_cmp_eq_u32_e64 s[2:3], 1, v81
	s_cbranch_vccz .LBB0_835
	s_lshl_b32 s15, s4, 6
	s_xor_b64 s[6:7], s[2:3], -1
	v_cmp_gt_i32_e32 vcc, s15, v150
	s_mul_i32 s5, s11, 0x4600
	s_or_b64 vcc, vcc, s[6:7]
	s_add_i32 s14, s5, 0
	v_add_u32_e32 v80, s14, v0
	s_mov_b64 s[4:5], vcc
	s_cmp_eq_u64 s[4:5], exec
	v_add_u32_e32 v119, v80, v171
	s_cbranch_scc1 .LBB0_829
	v_subrev_u32_e32 v120, s15, v117
	ds_read_b128 v[122:125], v119
	ds_read_b128 v[200:203], v119 offset:32
	ds_read_b128 v[204:207], v119 offset:64
	ds_read_b128 v[208:211], v119 offset:96
	v_cvt_f32_i32_e32 v80, v120
	s_or_b32 s4, s15, 31
	v_cmp_gt_i32_e64 s[4:5], s4, v150
	s_or_b64 s[4:5], s[6:7], s[4:5]
	v_mul_f32_e64 v80, -v152, v80
	v_cndmask_b32_e32 v94, v80, v164, vcc
	v_sub_f32_e32 v94, v94, v248
	v_fma_f32 v80, 0, v152, v94
	v_add_f32_e32 v81, v152, v94
	v_pk_fma_f32 v[82:83], v[152:153], s[72:73], v[94:95] op_sel_hi:[1,1,0]
	v_pk_fma_f32 v[84:85], v[152:153], s[74:75], v[94:95] op_sel_hi:[1,1,0]
	v_pk_fma_f32 v[86:87], v[152:153], s[76:77], v[94:95] op_sel_hi:[1,1,0]
	v_pk_fma_f32 v[88:89], v[152:153], s[70:71], v[94:95] op_sel_hi:[1,1,0]
	v_pk_fma_f32 v[90:91], v[152:153], s[78:79], v[94:95] op_sel_hi:[1,1,0]
	v_pk_fma_f32 v[92:93], v[152:153], s[80:81], v[94:95] op_sel_hi:[1,1,0]
	v_pk_fma_f32 v[94:95], v[152:153], s[82:83], v[94:95] op_sel_hi:[1,1,0]
	s_xor_b64 s[4:5], vcc, s[4:5]
	s_waitcnt lgkmcnt(3)
	v_mfma_f32_32x32x16_bf16 v[80:95], v[122:125], v[128:131], v[80:95]
	s_waitcnt lgkmcnt(2)
	v_mfma_f32_32x32x16_bf16 v[80:95], v[200:203], v[132:135], v[80:95]
	s_waitcnt lgkmcnt(1)
	v_mfma_f32_32x32x16_bf16 v[80:95], v[204:207], v[136:139], v[80:95]
	s_waitcnt lgkmcnt(0)
	v_mfma_f32_32x32x16_bf16 v[80:95], v[208:211], v[140:143], v[80:95]
	s_cmp_lg_u64 s[4:5], 0
	s_cbranch_scc0 .LBB0_826
	v_cmp_lt_i32_e32 vcc, -1, v120
	s_and_b64 vcc, s[2:3], vcc
	s_nop 8
	v_cndmask_b32_e32 v80, v164, v80, vcc
	v_cmp_lt_i32_e32 vcc, 0, v120
	s_and_b64 vcc, s[2:3], vcc
	s_nop 0
	v_cndmask_b32_e32 v81, v164, v81, vcc
	v_cmp_lt_i32_e32 vcc, 1, v120
	s_and_b64 vcc, s[2:3], vcc
	s_nop 0
	v_cndmask_b32_e32 v82, v164, v82, vcc
	v_cmp_lt_i32_e32 vcc, 2, v120
	s_and_b64 vcc, s[2:3], vcc
	s_nop 0
	v_cndmask_b32_e32 v83, v164, v83, vcc
	v_cmp_lt_i32_e32 vcc, 7, v120
	s_and_b64 vcc, s[2:3], vcc
	s_nop 0
	v_cndmask_b32_e32 v84, v164, v84, vcc
	v_cmp_lt_i32_e32 vcc, 8, v120
	s_and_b64 vcc, s[2:3], vcc
	s_nop 0
	v_cndmask_b32_e32 v85, v164, v85, vcc
	v_cmp_lt_i32_e32 vcc, 9, v120
	s_and_b64 vcc, s[2:3], vcc
	s_nop 0
	v_cndmask_b32_e32 v86, v164, v86, vcc
	v_cmp_lt_i32_e32 vcc, 10, v120
	s_and_b64 vcc, s[2:3], vcc
	s_nop 0
	v_cndmask_b32_e32 v87, v164, v87, vcc
	v_cmp_lt_i32_e32 vcc, 15, v120
	s_and_b64 vcc, s[2:3], vcc
	s_nop 0
	v_cndmask_b32_e32 v88, v164, v88, vcc
	v_cmp_lt_i32_e32 vcc, 16, v120
	s_and_b64 vcc, s[2:3], vcc
	s_nop 0
	v_cndmask_b32_e32 v89, v164, v89, vcc
	v_cmp_lt_i32_e32 vcc, 17, v120
	s_and_b64 vcc, s[2:3], vcc
	s_nop 0
	v_cndmask_b32_e32 v90, v164, v90, vcc
	v_cmp_lt_i32_e32 vcc, 18, v120
	s_and_b64 vcc, s[2:3], vcc
	s_nop 0
	v_cndmask_b32_e32 v91, v164, v91, vcc
	v_cmp_lt_i32_e32 vcc, 23, v120
	s_and_b64 vcc, s[2:3], vcc
	s_nop 0
	v_cndmask_b32_e32 v92, v164, v92, vcc
	v_cmp_lt_i32_e32 vcc, 24, v120
	s_and_b64 vcc, s[2:3], vcc
	s_nop 0
	v_cndmask_b32_e32 v93, v164, v93, vcc
	v_cmp_lt_i32_e32 vcc, 25, v120
	s_and_b64 vcc, s[2:3], vcc
	s_nop 0
	v_cndmask_b32_e32 v94, v164, v94, vcc
	v_cmp_lt_i32_e32 vcc, 26, v120
	s_and_b64 vcc, s[2:3], vcc
	s_nop 0
	v_cndmask_b32_e32 v95, v164, v95, vcc
